# phase-3 norm: post-norm gain vector loaded once before the row loop instead of four serialized loads per row
# speedup vs baseline: 1.0187x; 1.0039x over previous
.LBB0_267:
	s_andn2_b64 vcc, exec, s[0:1]
	s_cbranch_vccnz .LBB0_283
	s_cmp_gt_i32 s25, 2
	s_mov_b64 s[0:1], -1
	s_cbranch_scc0 .LBB0_281
	s_waitcnt vmcnt(0)
	v_ashrrev_i32_e32 v2, 6, v142
	v_readlane_b32 s0, v254, 0
	s_nop 1
	v_add_u32_e32 v6, s0, v2
	s_movk_i32 s0, 0x4100
	v_cmp_gt_i32_e32 vcc, s0, v6
	s_and_saveexec_b64 s[30:31], vcc
	s_cbranch_execz .LBB0_280
	v_and_b32_e32 v3, 63, v142
	v_readlane_b32 s0, v253, 45
	v_lshlrev_b32_e32 v0, 3, v3
	v_readlane_b32 s1, v253, 46
	v_lshlrev_b32_e32 v4, 2, v3
	v_xor_b32_e32 v23, 0x80, v4
	v_lshl_add_u64 v[8:9], s[0:1], 0, v[0:1]
	v_readlane_b32 s0, v251, 24
	v_readlane_b32 s1, v251, 25
	v_xor_b32_e32 v80, 64, v4
	v_xor_b32_e32 v81, 32, v4
	v_lshl_add_u64 v[10:11], s[0:1], 0, v[0:1]
	v_readlane_b32 s0, v251, 9
	v_readlane_b32 s1, v251, 10
	v_xor_b32_e32 v82, 16, v4
	v_xor_b32_e32 v83, 8, v4
	v_lshl_add_u64 v[12:13], s[0:1], 0, v[0:1]
	v_readlane_b32 s0, v253, 62
	v_readlane_b32 s1, v253, 63
	v_xor_b32_e32 v84, 4, v4
	v_lshlrev_b32_e32 v4, 4, v3
	v_mov_b32_e32 v5, v1
	v_lshl_add_u64 v[16:17], s[0:1], 0, v[0:1]
	v_readlane_b32 s0, v254, 1
	s_waitcnt lgkmcnt(0)
	v_lshl_add_u64 v[14:15], s[94:95], 0, v[4:5]
	global_load_dwordx4 v[118:121], v[14:15], off
	global_load_dwordx4 v[122:125], v[14:15], off offset:1024
	global_load_dwordx4 v[126:129], v[14:15], off offset:2048
	global_load_dwordx4 v[130:133], v[14:15], off offset:3072
	v_cmp_eq_u32_e32 vcc, 0, v3
	v_add_u32_e32 v0, s0, v2
	s_mov_b64 s[36:37], 0
	s_branch .LBB0_272

.LBB0_278:
	s_or_b64 exec, exec, s[0:1]
	v_pk_mul_f32 v[64:65], v[32:33], v[32:33]
	v_pk_mul_f32 v[66:67], v[28:29], v[28:29]
	v_pk_mul_f32 v[60:61], v[34:35], v[34:35]
	v_pk_mul_f32 v[62:63], v[30:31], v[30:31]
	v_mov_b32_e32 v68, v64
	v_mov_b32_e32 v69, v66
	v_mov_b32_e32 v66, v65
	v_pk_add_f32 v[64:65], v[68:69], v[66:67]
	v_mov_b32_e32 v66, v60
	v_mov_b32_e32 v67, v62
	v_pk_mul_f32 v[56:57], v[2:3], v[2:3]
	v_pk_mul_f32 v[58:59], v[24:25], v[24:25]
	v_pk_add_f32 v[64:65], v[66:67], v[64:65]
	v_mov_b32_e32 v62, v61
	v_pk_mul_f32 v[52:53], v[4:5], v[4:5]
	v_pk_mul_f32 v[54:55], v[26:27], v[26:27]
	v_pk_add_f32 v[60:61], v[62:63], v[64:65]
	v_mov_b32_e32 v62, v56
	v_mov_b32_e32 v63, v58
	v_mov_b32_e32 v58, v57
	v_pk_add_f32 v[56:57], v[62:63], v[58:59]
	v_mov_b32_e32 v58, v52
	v_mov_b32_e32 v59, v54
	v_pk_add_f32 v[56:57], v[58:59], v[56:57]
	v_mov_b32_e32 v54, v53
	v_pk_add_f32 v[52:53], v[54:55], v[56:57]
	v_add_f32_e32 v7, v60, v61
	v_add_f32_e32 v7, v53, v7
	v_add_f32_e32 v7, v52, v7
	ds_bpermute_b32 v52, v23, v7
	s_mov_b32 s2, 0x800000
	s_waitcnt vmcnt(3)
	v_lshlrev_b32_e32 v48, 16, v42
	v_and_b32_e32 v49, 0xffff0000, v42
	v_lshlrev_b32_e32 v50, 16, v43
	s_waitcnt lgkmcnt(0)
	v_add_f32_e32 v7, v7, v52
	ds_bpermute_b32 v52, v80, v7
	v_and_b32_e32 v51, 0xffff0000, v43
	s_waitcnt vmcnt(2)
	v_lshlrev_b32_e32 v44, 16, v40
	v_and_b32_e32 v45, 0xffff0000, v40
	v_lshlrev_b32_e32 v46, 16, v41
	s_waitcnt lgkmcnt(0)
	v_add_f32_e32 v7, v7, v52
	ds_bpermute_b32 v52, v81, v7
	v_and_b32_e32 v47, 0xffff0000, v41
	s_waitcnt vmcnt(1)
	v_lshlrev_b32_e32 v40, 16, v38
	v_and_b32_e32 v41, 0xffff0000, v38
	v_lshlrev_b32_e32 v42, 16, v39
	s_waitcnt lgkmcnt(0)
	v_add_f32_e32 v7, v7, v52
	ds_bpermute_b32 v52, v82, v7
	v_and_b32_e32 v43, 0xffff0000, v39
	s_waitcnt vmcnt(0)
	v_lshlrev_b32_e32 v38, 16, v36
	v_and_b32_e32 v39, 0xffff0000, v36
	v_lshlrev_b32_e32 v36, 16, v37
	s_waitcnt lgkmcnt(0)
	v_add_f32_e32 v7, v7, v52
	ds_bpermute_b32 v52, v83, v7
	v_and_b32_e32 v37, 0xffff0000, v37
	s_waitcnt lgkmcnt(0)
	v_add_f32_e32 v7, v7, v52
	ds_bpermute_b32 v52, v84, v7
	s_waitcnt lgkmcnt(0)
	v_add_f32_e32 v7, v7, v52
	v_fmamk_f32 v7, v7, 0x3a800000, v161
	v_cmp_gt_f32_e64 s[0:1], s2, v7
	v_mul_f32_e32 v52, 0x4b800000, v7
	s_nop 0
	v_cndmask_b32_e64 v7, v7, v52, s[0:1]
	v_rsq_f32_e32 v7, v7
	s_nop 0
	v_mul_f32_e32 v52, 0x45800000, v7
	v_cndmask_b32_e64 v7, v7, v52, s[0:1]
	v_mul_f32_e32 v52, 0.5, v7
	v_pk_mul_f32 v[54:55], v[34:35], v[52:53] op_sel_hi:[1,0]
	v_pk_mul_f32 v[56:57], v[32:33], v[52:53] op_sel_hi:[1,0]
	v_pk_mul_f32 v[56:57], v[118:119], v[56:57]
	v_pk_mul_f32 v[32:33], v[120:121], v[54:55]
	v_pk_fma_f32 v[34:35], v[22:23], v[48:49], v[56:57] op_sel_hi:[0,1,1]
	v_pk_fma_f32 v[32:33], v[22:23], v[50:51], v[32:33] op_sel_hi:[0,1,1]
	v_pk_mul_f32 v[48:49], v[30:31], v[52:53] op_sel_hi:[1,0]
	v_pk_mul_f32 v[50:51], v[28:29], v[52:53] op_sel_hi:[1,0]
	v_pk_mul_f32 v[50:51], v[122:123], v[50:51]
	v_pk_mul_f32 v[28:29], v[124:125], v[48:49]
	v_pk_fma_f32 v[30:31], v[22:23], v[44:45], v[50:51] op_sel_hi:[0,1,1]
	v_pk_fma_f32 v[28:29], v[22:23], v[46:47], v[28:29] op_sel_hi:[0,1,1]
	v_pk_mul_f32 v[44:45], v[26:27], v[52:53] op_sel_hi:[1,0]
	v_pk_mul_f32 v[46:47], v[24:25], v[52:53] op_sel_hi:[1,0]
	v_pk_mul_f32 v[46:47], v[126:127], v[46:47]
	v_pk_mul_f32 v[24:25], v[128:129], v[44:45]
	v_pk_fma_f32 v[26:27], v[22:23], v[40:41], v[46:47] op_sel_hi:[0,1,1]
	v_pk_fma_f32 v[24:25], v[22:23], v[42:43], v[24:25] op_sel_hi:[0,1,1]
	v_pk_mul_f32 v[40:41], v[4:5], v[52:53] op_sel_hi:[1,0]
	v_pk_mul_f32 v[42:43], v[2:3], v[52:53] op_sel_hi:[1,0]
	v_pk_mul_f32 v[2:3], v[130:131], v[42:43]
	v_pk_mul_f32 v[4:5], v[132:133], v[40:41]
	v_mov_b32_e32 v41, v27
	v_pk_fma_f32 v[4:5], v[22:23], v[36:37], v[4:5] op_sel_hi:[0,1,1]
	v_pk_fma_f32 v[36:37], v[22:23], v[38:39], v[2:3] op_sel_hi:[0,1,1]
	v_mov_b32_e32 v38, v35
	v_mov_b32_e32 v39, v31
	v_mov_b32_e32 v2, v34
	v_mov_b32_e32 v3, v30
	v_pk_mul_f32 v[38:39], v[38:39], v[38:39]
	v_mov_b32_e32 v40, v37
	v_pk_fma_f32 v[2:3], v[2:3], v[2:3], v[38:39]
	v_mov_b32_e32 v38, v32
	v_mov_b32_e32 v39, v28
	v_pk_fma_f32 v[2:3], v[38:39], v[38:39], v[2:3]
	v_mov_b32_e32 v38, v33
	v_mov_b32_e32 v39, v29
	v_pk_fma_f32 v[2:3], v[38:39], v[38:39], v[2:3]
	v_mov_b32_e32 v38, v36
	v_mov_b32_e32 v39, v26
	v_pk_mul_f32 v[40:41], v[40:41], v[40:41]
	v_add_f32_e32 v2, v2, v3
	v_pk_fma_f32 v[38:39], v[38:39], v[38:39], v[40:41]
	v_mov_b32_e32 v40, v4
	v_mov_b32_e32 v41, v24
	v_pk_fma_f32 v[38:39], v[40:41], v[40:41], v[38:39]
	v_mov_b32_e32 v40, v5
	v_mov_b32_e32 v41, v25
	v_pk_fma_f32 v[38:39], v[40:41], v[40:41], v[38:39]
	s_nop 0
	v_add_f32_e32 v2, v39, v2
	v_add_f32_e32 v2, v38, v2
	ds_bpermute_b32 v3, v23, v2
	s_waitcnt lgkmcnt(0)
	v_add_f32_e32 v2, v2, v3
	ds_bpermute_b32 v3, v80, v2
	s_waitcnt lgkmcnt(0)
	v_add_f32_e32 v2, v2, v3
	ds_bpermute_b32 v3, v81, v2
	s_waitcnt lgkmcnt(0)
	v_add_f32_e32 v2, v2, v3
	ds_bpermute_b32 v3, v82, v2
	s_waitcnt lgkmcnt(0)
	v_add_f32_e32 v2, v2, v3
	ds_bpermute_b32 v3, v83, v2
	s_waitcnt lgkmcnt(0)
	v_add_f32_e32 v2, v2, v3
	ds_bpermute_b32 v3, v84, v2
	s_waitcnt lgkmcnt(0)
	v_add_f32_e32 v2, v2, v3
	v_fmamk_f32 v3, v2, 0x3a800000, v161
	v_cmp_gt_f32_e64 s[0:1], s2, v3
	v_mul_f32_e32 v2, 0x4b800000, v3
	s_nop 0
	v_cndmask_b32_e64 v2, v3, v2, s[0:1]
	v_rsq_f32_e32 v2, v2
	s_nop 0
	v_mul_f32_e32 v7, 0x45800000, v2
	v_cndmask_b32_e64 v2, v2, v7, s[0:1]
	v_pk_mul_f32 v[34:35], v[34:35], v[2:3] op_sel_hi:[1,0]
	v_pk_mul_f32 v[30:31], v[30:31], v[2:3] op_sel_hi:[1,0]
	v_pk_mul_f32 v[24:25], v[24:25], v[2:3] op_sel_hi:[1,0]
	v_pk_mul_f32 v[26:27], v[26:27], v[2:3] op_sel_hi:[1,0]
	v_pk_mul_f32 v[32:33], v[32:33], v[2:3] op_sel_hi:[1,0]
	v_cvt_pk_bf16_f32 v34, v34, v35
	v_pk_mul_f32 v[28:29], v[28:29], v[2:3] op_sel_hi:[1,0]
	v_cvt_pk_bf16_f32 v35, v32, v33
	global_store_dwordx2 v[20:21], v[34:35], off
	v_cvt_pk_bf16_f32 v30, v30, v31
	v_cvt_pk_bf16_f32 v31, v28, v29
	global_store_dwordx2 v[20:21], v[30:31], off offset:512
	v_cvt_pk_bf16_f32 v26, v26, v27
	v_cvt_pk_bf16_f32 v27, v24, v25
	v_pk_mul_f32 v[24:25], v[36:37], v[2:3] op_sel_hi:[1,0]
	global_store_dwordx2 v[20:21], v[26:27], off offset:1024
	v_pk_mul_f32 v[4:5], v[4:5], v[2:3] op_sel_hi:[1,0]
	v_cvt_pk_bf16_f32 v24, v24, v25
	s_nop 0
	v_cvt_pk_bf16_f32 v25, v4, v5
	global_store_dwordx2 v[20:21], v[24:25], off offset:1536
	s_and_saveexec_b64 s[0:1], vcc
	s_cbranch_execz .LBB0_271
	v_mul_f32_e32 v2, v3, v2
	global_store_dword v[18:19], v2, off
	s_branch .LBB0_271
